# grid barrier leader: no wait on the acknowledgement of the XCD generation increment; early agent-scope invalidate
# speedup vs baseline: 1.0091x; 1.0091x over previous
; __device__ __forceinline__ unsigned xb_add(unsigned* p, unsigned v) { return __hip_atomic_fetch_add(p, v, __ATOMIC_RELAXED, __HIP_MEMORY_SCOPE_AGENT); }
; __device__ __forceinline__ void xcd_barrier(unsigned* bar, volatile LAS unsigned* st, const int tid) {
;     ...
;             __builtin_amdgcn_fence(__ATOMIC_ACQUIRE, "agent");
;             xb_add(&bar[XB_XGEN(x)], 1u);
;             asm volatile("s_waitcnt vmcnt(0)" ::: "memory");
.LBB0_101:
	s_or_b64 exec, exec, s[22:23]
.LBB0_102:
	s_or_b64 exec, exec, s[12:13]
	s_mov_b64 s[12:13], 0
	s_barrier
